# P0 w_in transposes: next tile's loads issued at the loop top right behind the pk_mul that frees each register (scalar tile base + loop-invariant row offsets) instead of after the LDS write, barrier an
# baseline (speedup 1.0000x reference)
.LBB0_47:
	v_or_b32_e32 v33, 0x80, v161
	s_lshl_b32 s29, s2, 8
	s_lshl_b32 s33, s30, 8
	v_lshl_add_u32 v35, v160, 1, s62
	s_lshl_b32 s34, s30, 9
	v_add_u32_e32 v37, v159, v162
	v_mov_b32_e32 v129, 0
	s_movk_i32 s35, 0x7ff
	s_movk_i32 s58, 0xfff
	s_movk_i32 s59, 0x1800
	s_mov_b32 s60, 0x7fffff00
	s_movk_i32 s61, 0xff00
	v_lshlrev_b32_e32 v38, 1, v213
	s_mov_b32 s64, s2
	v_mul_u32_u24_e32 v96, 0xa000, v176
	v_add_u32_e32 v96, v96, v128
	v_add_u32_e32 v97, 0x50000, v96
	v_add_u32_e32 v98, 0xa0000, v96
	v_add_u32_e32 v99, 0xf0000, v96
	v_add_u32_e32 v100, 0x140000, v96
	v_add_u32_e32 v101, 0x190000, v96
	v_add_u32_e32 v102, 0x1e0000, v96
	v_add_u32_e32 v103, 0x230000, v96
	v_lshlrev_b32_e32 v104, 2, v176
	s_waitcnt vmcnt(0)
	s_branch .LBB0_49

.LBB0_49:
	s_add_i32 s63, s64, s30
	s_cmpk_gt_i32 s63, 0x4ff
	s_cbranch_scc1 .Lp0_old
	s_and_b64 vcc, exec, s[0:1]
	s_cbranch_vccnz .Lp0_old
	s_mov_b64 s[4:5], 0
	s_mul_hi_i32 s3, s63, 0x66666667
	s_lshr_b32 s6, s3, 31
	s_ashr_i32 s3, s3, 4
	s_add_i32 s3, s3, s6
	s_mul_i32 s6, s3, 40
	s_sub_i32 s6, s63, s6
	s_lshl_b32 s6, s6, 10
	s_mul_i32 s8, s3, 0x280000
	s_add_i32 s6, s6, s8
	s_add_u32 s6, s22, s6
	s_addc_u32 s7, s23, 0
	s_lshl_b32 s8, s3, 8
	s_add_u32 s8, s20, s8
	s_addc_u32 s9, s21, 0
	s_waitcnt vmcnt(18)
	v_pk_mul_f32 v[52:53], v[2:3], v[32:33] op_sel_hi:[1,0]
	v_pk_mul_f32 v[50:51], v[0:1], v[32:33] op_sel_hi:[1,0]
	ds_write_b128 v37, v[50:53]
	global_load_dwordx4 v[0:3], v96, s[6:7] nt
	global_load_dword v32, v104, s[8:9]
	s_waitcnt vmcnt(18)
	v_pk_mul_f32 v[52:53], v[6:7], v[34:35] op_sel_hi:[1,0]
	v_pk_mul_f32 v[50:51], v[4:5], v[34:35] op_sel_hi:[1,0]
	ds_write_b128 v37, v[50:53] offset:8320
	global_load_dwordx4 v[4:7], v97, s[6:7] nt
	global_load_dword v34, v104, s[8:9] offset:32
	s_waitcnt vmcnt(18)
	v_pk_mul_f32 v[52:53], v[10:11], v[36:37] op_sel_hi:[1,0]
	v_pk_mul_f32 v[50:51], v[8:9], v[36:37] op_sel_hi:[1,0]
	ds_write_b128 v37, v[50:53] offset:16640
	global_load_dwordx4 v[8:11], v98, s[6:7] nt
	global_load_dword v36, v104, s[8:9] offset:64
	s_waitcnt vmcnt(18)
	v_pk_mul_f32 v[52:53], v[14:15], v[40:41] op_sel_hi:[1,0]
	v_pk_mul_f32 v[50:51], v[12:13], v[40:41] op_sel_hi:[1,0]
	ds_write_b128 v37, v[50:53] offset:24960
	global_load_dwordx4 v[12:15], v99, s[6:7] nt
	global_load_dword v40, v104, s[8:9] offset:96
	s_waitcnt vmcnt(18)
	v_pk_mul_f32 v[52:53], v[18:19], v[42:43] op_sel_hi:[1,0]
	v_pk_mul_f32 v[50:51], v[16:17], v[42:43] op_sel_hi:[1,0]
	ds_write_b128 v37, v[50:53] offset:33280
	global_load_dwordx4 v[16:19], v100, s[6:7] nt
	global_load_dword v42, v104, s[8:9] offset:128
	s_waitcnt vmcnt(18)
	v_pk_mul_f32 v[52:53], v[22:23], v[44:45] op_sel_hi:[1,0]
	v_pk_mul_f32 v[50:51], v[20:21], v[44:45] op_sel_hi:[1,0]
	ds_write_b128 v37, v[50:53] offset:41600
	global_load_dwordx4 v[20:23], v101, s[6:7] nt
	global_load_dword v44, v104, s[8:9] offset:160
	s_waitcnt vmcnt(18)
	v_pk_mul_f32 v[52:53], v[26:27], v[46:47] op_sel_hi:[1,0]
	v_pk_mul_f32 v[50:51], v[24:25], v[46:47] op_sel_hi:[1,0]
	ds_write_b128 v37, v[50:53] offset:49920
	global_load_dwordx4 v[24:27], v102, s[6:7] nt
	global_load_dword v46, v104, s[8:9] offset:192
	s_waitcnt vmcnt(18)
	v_pk_mul_f32 v[52:53], v[30:31], v[48:49] op_sel_hi:[1,0]
	v_pk_mul_f32 v[50:51], v[28:29], v[48:49] op_sel_hi:[1,0]
	ds_write_b128 v37, v[50:53] offset:58240
	global_load_dwordx4 v[28:31], v103, s[6:7] nt
	global_load_dword v48, v104, s[8:9] offset:224
	s_waitcnt lgkmcnt(0)
	s_barrier
	s_branch .LBB0_63
